# MLA loop: K fragment prefetch one phase ahead, LDS-DMA issue with scalar addressing and rebalanced pieces, static priority for waves 4-7
# speedup vs baseline: 1.0860x; 1.0293x over previous
; DEVINL void partialSM(f32x16& p0, f32x16& p1, float& m_reg, float& mn, float& alpha, int kvalid, int hi) {
;   constexpr float C = MLA_SCALE * 1.4426950408889634f;
;   if (kvalid < 64) {
; #pragma unroll
;     for (int r = 0; r < 16; ++r) { if (crow(r, hi) >= kvalid) p0[r] = -1e30f; if (32 + crow(r, hi) >= kvalid) p1[r] = -1e30f; }
;   }
;   float pmax = p0[0];
; #pragma unroll
;   for (int r = 1; r < 16; ++r) pmax = fmaxf(pmax, p0[r]);
; #pragma unroll
;   for (int r = 0; r < 16; ++r) pmax = fmaxf(pmax, p1[r]);
;   { auto rr = __builtin_amdgcn_permlane32_swap(__float_as_uint(pmax), __float_as_uint(pmax), false, false);
;     pmax = fmaxf(__uint_as_float(rr[0]), __uint_as_float(rr[1])); }
;   if (__builtin_expect(__all(pmax - m_reg <= THR / MLA_SCALE), 1)) { mn = m_reg; alpha = 1.f; }
;   else { mn = fmaxf(m_reg, pmax); alpha = __builtin_amdgcn_exp2f((m_reg - mn) * C); m_reg = mn; }
;   const float mnC = PSHIFT - mn * C;
;   const f32x2 C2 = {C, C}, M2 = {mnC, mnC};
; #pragma unroll
;   for (int r = 0; r < 16; r += 2) { f32x2 v = {p0[r], p0[r + 1]}; v = __builtin_elementwise_fma(v, C2, M2); p0[r] = v[0]; p0[r + 1] = v[1]; }
; #pragma unroll
; template <bool FUSE>
; DEVINL void qkt(f32x16& p0, f32x16& p1, const char* Ks, const i32x8* q8, int r32, int hi, f32x16& e1) {
;   p0 = f32x16{}; p1 = f32x16{};
;   const char* ka = Ks + hi * 1024 + r32 * 16; const char* kb = Ks + 4096 + hi * 512 + r32 * 8;
;   const char* ra = Ks + 6144 + hi * 1024 + r32 * 16; const char* rb = Ks + 6144 + 2048 + hi * 512 + r32 * 8;
;   u32x4 fa[3][2]; u32x2 fb[3][2];
;     ...
;   QK_LD(0, 0);
; #pragma unroll
;   for (int t = 0; t < 3; ++t) {
;     if (t + 1 < 3) QK_LD(t + 1, (t + 1) % 3);
;     const i32x8 a0 = mk6((int)fa[t][0][0], (int)fa[t][0][1], (int)fa[t][0][2], (int)fa[t][0][3], (int)fb[t][0][0], (int)fb[t][0][1]);
;     const i32x8 a1 = mk6((int)fa[t][1][0], (int)fa[t][1][1], (int)fa[t][1][2], (int)fa[t][1][3], (int)fb[t][1][0], (int)fb[t][1][1]);
;     p0 = MFMA6(a0, q8[t], p0);
;     if (FUSE) {
; #pragma unroll
;       for (int r = 0; r < 3; ++r) { const int rr = t * 6 + r; if (rr < 16) e1[rr] = __builtin_amdgcn_exp2f(e1[rr]); }
;     }
;     p1 = MFMA6(a1, q8[t], p1);
;     if (FUSE) {
; #pragma unroll
;       for (int r = 3; r < 6; ++r) { const int rr = t * 6 + r; if (rr < 16) e1[rr] = __builtin_amdgcn_exp2f(e1[rr]); }
;     }
;     SBAR();
;   }
;     ...
; }
.LBB0_559:
	s_or_b64 exec, exec, s[8:9]
	s_mul_i32 s8, s75, 0x208000
	s_add_u32 s14, s58, s8
	v_add_u32_e32 v0, 0x9000, v172
	s_addc_u32 s15, s59, 0
	v_readfirstlane_b32 s9, v0
	v_add_u32_e32 v2, 0xb000, v172
	v_lshl_add_u64 v[140:141], s[14:15], 0, v[138:139]
	s_mov_b32 m0, s9
	v_readfirstlane_b32 s9, v2
	global_load_lds_dwordx4 v[140:141], off
	v_lshl_add_u64 v[0:1], v[140:141], 0, s[48:49]
	s_mov_b32 m0, s9
	v_lshlrev_b32_e32 v170, 9, v48
	global_load_lds_dwordx4 v[0:1], off
	v_and_b32_e32 v0, 0x3fffffc0, v166
	v_lshl_add_u32 v171, v0, 2, s68
	v_add_u32_e32 v0, 0, v170
	v_lshlrev_b32_e32 v176, 3, v167
	v_lshlrev_b32_e32 v175, 4, v167
	v_add_u32_e32 v49, v0, v176
	v_add3_u32 v173, v0, v170, v175
	v_add_u32_e32 v0, 0x1000, v49
	s_waitcnt vmcnt(0)
	s_waitcnt vmcnt(0) lgkmcnt(0)
	s_barrier
	ds_read2_b64 v[4:7], v0 offset1:32
	ds_read_b128 v[50:53], v173 offset:2048
	ds_read_b128 v[56:59], v173 offset:2560
	ds_read2_b64 v[60:63], v0 offset0:128 offset1:160
	ds_read_b128 v[16:19], v173 offset:512
	ds_read_b128 v[0:3], v173
	s_waitcnt lgkmcnt(5)
	v_mov_b32_e32 v20, v6
	v_mov_b32_e32 v21, v7
	s_waitcnt lgkmcnt(0)
	v_mfma_scale_f32_32x32x64_f8f6f4 v[32:47], v[0:5], v[120:125], 0, v162, v162 op_sel_hi:[0,0,0] cbsz:2 blgp:2
	s_mov_b32 s12, s13
	s_mov_b32 s14, s13
	s_mov_b32 s15, s13
	s_mov_b32 s16, s13
	s_mov_b32 s17, s13
	s_mov_b32 s18, s13
	s_mov_b32 s19, s13
	v_mfma_scale_f32_32x32x64_f8f6f4 v[16:31], v[16:21], v[120:125], 0, v162, v162 op_sel_hi:[0,0,0] cbsz:2 blgp:2
	s_mov_b32 s20, s13
	s_mov_b32 s21, s13
	s_mov_b32 s22, s13
	s_mov_b32 s23, s13
	s_mov_b32 s24, s13
	s_mov_b32 s25, s13
	s_mov_b32 s26, s13
	s_mov_b32 s27, s13
	v_mov_b64_e32 v[0:1], s[12:13]
	v_and_b32_e32 v169, 63, v166
	v_lshlrev_b32_e32 v174, 10, v48
	s_mov_b32 s53, 4
	v_mov_b64_e32 v[2:3], s[14:15]
	v_mov_b64_e32 v[4:5], s[16:17]
	v_mov_b64_e32 v[6:7], s[18:19]
	v_mov_b64_e32 v[8:9], s[20:21]
	v_mov_b64_e32 v[10:11], s[22:23]
	v_mov_b64_e32 v[12:13], s[24:25]
	v_mov_b64_e32 v[14:15], s[26:27]
	v_mov_b32_e32 v54, v60
	v_mov_b32_e32 v55, v61
	v_mov_b32_e32 v60, v62
	v_mov_b32_e32 v61, v63
	v_add_u32_e32 v49, 0x2000, v49
	v_mfma_scale_f32_32x32x64_f8f6f4 v[32:47], v[50:55], v[126:131], v[32:47], v162, v162 op_sel_hi:[0,0,0] cbsz:2 blgp:2
	ds_read_b128 v[50:53], v173 offset:6144
	ds_read_b128 v[62:65], v173 offset:6656
	ds_read2_b64 v[66:69], v49 offset1:32
	v_mfma_scale_f32_32x32x64_f8f6f4 v[16:31], v[56:61], v[126:131], v[16:31], v162, v162 op_sel_hi:[0,0,0] cbsz:2 blgp:2
	s_waitcnt lgkmcnt(0)
	v_mov_b32_e32 v54, v66
	v_mov_b32_e32 v55, v67
	v_mov_b32_e32 v66, v68
	v_mov_b32_e32 v67, v69
	v_mfma_scale_f32_32x32x64_f8f6f4 v[32:47], v[50:55], v[132:137], v[32:47], v162, v162 op_sel_hi:[0,0,0] cbsz:2 blgp:2
	s_nop 0
	v_mfma_scale_f32_32x32x64_f8f6f4 v[16:31], v[62:67], v[132:137], v[16:31], v162, v162 op_sel_hi:[0,0,0] cbsz:2 blgp:2
	s_nop 9
	v_max_f32_e32 v49, v33, v33
	v_max_f32_e32 v50, v32, v32
	v_max_f32_e32 v49, v50, v49
	v_max3_f32 v49, v49, v34, v35
	v_max3_f32 v49, v49, v36, v37
	v_max3_f32 v49, v49, v38, v39
	v_max3_f32 v49, v49, v40, v41
	v_max3_f32 v49, v49, v42, v43
	v_max3_f32 v49, v49, v44, v45
	v_max3_f32 v49, v49, v46, v47
	v_max3_f32 v49, v49, v16, v17
	v_max3_f32 v49, v49, v18, v19
	v_max3_f32 v49, v49, v20, v21
	v_max3_f32 v49, v49, v22, v23
	v_max3_f32 v49, v49, v24, v25
	v_max3_f32 v49, v49, v26, v27
	v_max3_f32 v49, v49, v28, v29
	v_max3_f32 v49, v49, v30, v31
	v_mov_b32_e32 v50, v49
	s_nop 1
	v_permlane32_swap_b32_e32 v49, v50
	v_max_f32_e32 v50, v50, v50
	v_max_f32_e32 v49, v49, v49
	v_max_f32_e32 v49, v49, v50
	v_add_f32_e32 v50, 0x7149f2ca, v49
	v_max_f32_e32 v49, 0xf149f2ca, v49
	v_sub_f32_e32 v51, 0xf149f2ca, v49
	v_mul_f32_e32 v51, 0x3dd53b94, v51
	v_cmp_ge_f32_e32 vcc, s69, v50
	v_exp_f32_e32 v51, v51
	s_cmp_eq_u64 vcc, exec
	s_cselect_b64 vcc, -1, 0
	v_cndmask_b32_e32 v181, v49, v163, vcc
	v_fmamk_f32 v50, v181, 0xbdd53b94, v164
	v_pk_fma_f32 v[32:33], v[32:33], s[50:51], v[50:51] op_sel_hi:[1,0,0]
	v_pk_fma_f32 v[34:35], v[34:35], s[50:51], v[50:51] op_sel_hi:[1,0,0]
	v_pk_fma_f32 v[36:37], v[36:37], s[50:51], v[50:51] op_sel_hi:[1,0,0]
	v_pk_fma_f32 v[38:39], v[38:39], s[50:51], v[50:51] op_sel_hi:[1,0,0]
	v_pk_fma_f32 v[40:41], v[40:41], s[50:51], v[50:51] op_sel_hi:[1,0,0]
	v_pk_fma_f32 v[42:43], v[42:43], s[50:51], v[50:51] op_sel_hi:[1,0,0]
	v_pk_fma_f32 v[44:45], v[44:45], s[50:51], v[50:51] op_sel_hi:[1,0,0]
	v_pk_fma_f32 v[46:47], v[46:47], s[50:51], v[50:51] op_sel_hi:[1,0,0]
	v_exp_f32_e32 v65, v32
	v_exp_f32_e32 v197, v33
	v_exp_f32_e32 v187, v34
	v_exp_f32_e32 v189, v35
	v_exp_f32_e32 v195, v36
	v_exp_f32_e32 v196, v37
	v_exp_f32_e32 v191, v38
	v_exp_f32_e32 v192, v39
	v_exp_f32_e32 v193, v40
	v_exp_f32_e32 v194, v41
	v_exp_f32_e32 v183, v42
	v_exp_f32_e32 v184, v43
	v_exp_f32_e32 v188, v44
	v_exp_f32_e32 v190, v45
	v_exp_f32_e32 v185, v46
	v_exp_f32_e32 v186, v47
	s_add_u32 s8, s30, s8
	v_cndmask_b32_e64 v179, v51, 1.0, vcc
	v_pk_fma_f32 v[148:149], v[30:31], s[50:51], v[50:51] op_sel_hi:[1,0,0]
	v_pk_fma_f32 v[150:151], v[28:29], s[50:51], v[50:51] op_sel_hi:[1,0,0]
	v_pk_fma_f32 v[152:153], v[26:27], s[50:51], v[50:51] op_sel_hi:[1,0,0]
	v_pk_fma_f32 v[154:155], v[24:25], s[50:51], v[50:51] op_sel_hi:[1,0,0]
	v_pk_fma_f32 v[156:157], v[22:23], s[50:51], v[50:51] op_sel_hi:[1,0,0]
	v_pk_fma_f32 v[82:83], v[20:21], s[50:51], v[50:51] op_sel_hi:[1,0,0]
	v_pk_fma_f32 v[158:159], v[18:19], s[50:51], v[50:51] op_sel_hi:[1,0,0]
	v_pk_fma_f32 v[160:161], v[16:17], s[50:51], v[50:51] op_sel_hi:[1,0,0]
	v_lshlrev_b32_e32 v177, 4, v48
	s_addc_u32 s9, s31, 0
	v_mov_b64_e32 v[62:63], v[14:15]
	v_mov_b64_e32 v[30:31], v[14:15]
; #define SBAR() __builtin_amdgcn_sched_barrier(0)
; DEVINL i32x8 mk6(int a, int b, int c, int d, int e, int f) { i32x8 r = __builtin_nondeterministic_value(r); r[0] = a; r[1] = b; r[2] = c; r[3] = d; r[4] = e; r[5] = f; return r; }
; #define MFMA6(A, B, C) __builtin_amdgcn_mfma_scale_f32_32x32x64_f8f6f4(A, B, C, 2, 2, 0, 0x7f7f7f7f, 0, 0x7f7f7f7f)
; #define ISSUE_K(j) do { const int _t = (j) < NT ? (j) : NT - 1; char* _d = K_lds + ((j) & 3) * SHM_K8; if (wid < 6) GLDS(K8 + (size_t)_t * 6144 + t16u, _d + tid16); \
;     if (wid < 3) GLDS(Kp8 + (size_t)_t * 3072 + t16u, _d + 6144 + tid16); } while (0)
; template <bool FUSE>
; DEVINL void qkt(f32x16& p0, f32x16& p1, const char* Ks, const i32x8* q8, int r32, int hi, f32x16& e1) {
;   p0 = f32x16{}; p1 = f32x16{};
;   const char* ka = Ks + hi * 1024 + r32 * 16; const char* kb = Ks + 4096 + hi * 512 + r32 * 8;
;   const char* ra = Ks + 6144 + hi * 1024 + r32 * 16; const char* rb = Ks + 6144 + 2048 + hi * 512 + r32 * 8;
;   u32x4 fa[3][2]; u32x2 fb[3][2];
;     ...
;   QK_LD(0, 0);
; #pragma unroll
;   for (int t = 0; t < 3; ++t) {
;     if (t + 1 < 3) QK_LD(t + 1, (t + 1) % 3);
;     const i32x8 a0 = mk6((int)fa[t][0][0], (int)fa[t][0][1], (int)fa[t][0][2], (int)fa[t][0][3], (int)fb[t][0][0], (int)fb[t][0][1]);
;     const i32x8 a1 = mk6((int)fa[t][1][0], (int)fa[t][1][1], (int)fa[t][1][2], (int)fa[t][1][3], (int)fb[t][1][0], (int)fb[t][1][1]);
;     p0 = MFMA6(a0, q8[t], p0);
; DEVINL void mla_block(const Params& p, const bf16_t* __restrict__ Qn, const bf16_t* __restrict__ Qr, const char* __restrict__ K8, const char* __restrict__ Kp8,
;                       const char* __restrict__ V8, const bf16_t* __restrict__ Gb, bf16_t* __restrict__ Yb, char* lds, int pos0) {
;     ...
;   f32x16 pA0, pA1, pB0, pB1; float mnA, mnB, alA, alB; i32x8 pa; VFrag vf; constexpr int NT = NT_MLA;
;   const i32x8 ones8 = {0x38383838, 0x38383838, 0x38383838, 0x38383838, 0x38383838, 0x38383838, 0x38383838, 0x38383838};
;   f32x16 lsum;
;     ...
;   ISSUE_K(0); ISSUE_K(1); ISSUE_K(2); ISSUE_V(0); ISSUE_V(1); TILE_SYNC();
;   qkt<false>(pA0, pA1, KS(0), q8, r32, hi, pA1); partialSM(pA0, pA1, m_reg, mnA, alA, 64, hi);
;   for (int j = 1; j + 1 < NT; j += 2) {
;     ISSUE_K(j + 2); ISSUE_K(j + 3); ISSUE_V(j + 1); ISSUE_V(j + 2); SBAR();
;     qkt<true>(pB0, pB1, KS(j), q8, r32, hi, pA1);
	v_mov_b64_e32 v[46:47], v[14:15]
	v_lshl_add_u64 v[142:143], s[6:7], 0, v[138:139]
	v_lshl_add_u64 v[144:145], s[34:35], 0, v[138:139]
	v_cmp_gt_u32_e64 s[6:7], 32, v169
	v_lshl_add_u32 v178, v167, 2, v171
	v_lshl_add_u64 v[146:147], s[8:9], 0, v[138:139]
	v_mov_b32_e32 v180, 0
	s_mov_b64 s[14:15], 0x89dc400
	v_mov_b64_e32 v[60:61], v[12:13]
	v_mov_b64_e32 v[58:59], v[10:11]
	v_mov_b64_e32 v[56:57], v[8:9]
	v_mov_b64_e32 v[54:55], v[6:7]
	v_mov_b64_e32 v[52:53], v[4:5]
	v_mov_b64_e32 v[50:51], v[2:3]
	v_mov_b64_e32 v[48:49], v[0:1]
	v_mov_b64_e32 v[28:29], v[12:13]
	v_mov_b64_e32 v[26:27], v[10:11]
	v_mov_b64_e32 v[24:25], v[8:9]
	v_mov_b64_e32 v[22:23], v[6:7]
	v_mov_b64_e32 v[20:21], v[4:5]
	v_mov_b64_e32 v[18:19], v[2:3]
	v_mov_b64_e32 v[16:17], v[0:1]
	v_mov_b64_e32 v[44:45], v[12:13]
	v_mov_b64_e32 v[42:43], v[10:11]
	v_mov_b64_e32 v[40:41], v[8:9]
	v_mov_b64_e32 v[38:39], v[6:7]
	v_mov_b64_e32 v[36:37], v[4:5]
	v_mov_b64_e32 v[34:35], v[2:3]
	v_mov_b64_e32 v[32:33], v[0:1]
	v_mov_b32_e32 v232, v112
	v_mov_b32_e32 v233, v112
	v_mov_b32_e32 v234, v112
	v_mov_b32_e32 v235, v112
	v_mov_b32_e32 v236, v112
	v_mov_b32_e32 v237, v112
	v_mov_b32_e32 v238, v112
	v_mov_b32_e32 v239, v112
	v_add_u32_e32 v176, v170, v176
	v_add_u32_e32 v176, 0x1000, v176
	v_add_u32_e32 v174, 0x2400, v173
	v_add_u32_e32 v175, 0x2400, v176
	ds_read_b128 v[204:207], v174
	ds_read_b64 v[208:209], v175
	ds_read_b128 v[216:219], v174 offset:512
	ds_read_b64 v[220:221], v175 offset:256
	s_lshl_b32 s78, s3, 4
	s_add_i32 s79, s78, 0x9000
	s_mul_i32 s80, s75, 0x186000
	s_add_u32 s80, s56, s80
	s_addc_u32 s81, s57, 0
	s_mov_b64 s[82:83], s[34:35]
	s_mul_i32 s84, s75, 0x208000
	s_add_u32 s84, s58, s84
	s_addc_u32 s85, s59, 0
	v_lshlrev_b32_e32 v231, 4, v169
	s_cmp_ge_u32 s3, 0x100
	s_cbranch_scc0 .Lprio_skip
	s_setprio 2
.Lprio_skip:
.LBB0_560:
	s_add_i32 s8, s53, -1
	s_cmpk_lg_i32 s53, 0x102
	s_cselect_b32 s17, s8, 0x100
	s_and_b32 s16, s8, 3
	s_add_i32 s18, s53, -3
	s_cmpk_lt_u32 s18, 0xfe
	s_cselect_b32 s86, s53, 0x100
	s_and_b32 s87, s53, 3
	s_add_i32 s19, s53, -2
	s_and_b32 s20, s19, 3
	s_lshl_b32 s88, s19, 13
	s_add_u32 s88, s88, s78
	s_add_u32 s90, s84, s88
	s_addc_u32 s91, s85, 0
	s_lshl_b32 s89, s20, 13
	s_add_i32 s89, s89, s79
	s_mov_b32 m0, s89
	s_lshl_b32 s88, s17, 13
	global_load_lds_dwordx4 v231, s[90:91]
	s_add_u32 s88, s88, s78
	s_add_u32 s90, s84, s88
	s_addc_u32 s91, s85, 0
	s_lshl_b32 s89, s16, 13
	s_add_i32 s89, s89, s79
	s_mov_b32 m0, s89
	s_cmp_ge_u32 s3, 0x180
	global_load_lds_dwordx4 v231, s[90:91]
	s_cbranch_scc1 .Ldma_rope
	s_mul_i32 s88, s17, 0x1800
	s_add_u32 s88, s88, s78
	s_add_u32 s90, s80, s88
	s_addc_u32 s91, s81, 0
	s_mul_i32 s89, s16, 0x2400
	s_add_i32 s89, s89, s78
	s_mov_b32 m0, s89
	s_mul_i32 s88, s86, 0x1800
	global_load_lds_dwordx4 v231, s[90:91]
	s_add_u32 s88, s88, s78
	s_add_u32 s90, s80, s88
	s_addc_u32 s91, s81, 0
	s_mul_i32 s89, s87, 0x2400
	s_add_i32 s89, s89, s78
	s_mov_b32 m0, s89
	s_nop 0
	global_load_lds_dwordx4 v231, s[90:91]
	s_branch .Ldma_done
.Ldma_rope:
	s_cmp_ge_u32 s3, 0x1c0
	s_cselect_b32 s88, s86, s17
	s_cselect_b32 s89, s87, s16
	s_mul_i32 s88, s88, 0xc00
	s_add_u32 s90, s82, s88
	s_addc_u32 s91, s83, 0
	s_mul_i32 s89, s89, 0x2400
	s_add_i32 s89, s89, 0x1800
	s_mov_b32 m0, s89
	s_add_i32 s89, s89, 0x400
	global_load_lds_dwordx4 v231, s[90:91]
	s_add_u32 s90, s90, 0x400
	s_addc_u32 s91, s91, 0
	s_mov_b32 m0, s89
	s_add_i32 s89, s89, 0x400
	global_load_lds_dwordx4 v231, s[90:91]
	s_add_u32 s90, s90, 0x400
	s_addc_u32 s91, s91, 0
	s_mov_b32 m0, s89
	s_nop 0
	global_load_lds_dwordx4 v231, s[90:91]
.Ldma_done:
	s_and_b32 s12, s18, 3
	ds_read_b128 v[114:117], v174 offset:2048
	ds_read_b128 v[198:201], v174 offset:2560
	ds_read_b64 v[118:119], v175 offset:1024
	ds_read_b64 v[202:203], v175 offset:1280
	v_exp_f32_e32 v182, v82
	s_waitcnt lgkmcnt(4)
	v_exp_f32_e32 v214, v83
	v_mfma_scale_f32_32x32x64_f8f6f4 v[96:111], v[204:209], v[120:125], 0, v162, v162 op_sel_hi:[0,0,0] cbsz:2 blgp:2
	v_exp_f32_e32 v160, v160
	v_exp_f32_e32 v161, v161
	v_exp_f32_e32 v158, v158
	v_exp_f32_e32 v159, v159
	v_mfma_scale_f32_32x32x64_f8f6f4 v[80:95], v[216:221], v[120:125], 0, v162, v162 op_sel_hi:[0,0,0] cbsz:2 blgp:2
	ds_read_b128 v[66:69], v174 offset:6144
	ds_read_b128 v[72:75], v174 offset:6656
	ds_read_b64 v[70:71], v175 offset:4096
	ds_read_b64 v[76:77], v175 offset:4352
	s_waitcnt lgkmcnt(4)
	v_mfma_scale_f32_32x32x64_f8f6f4 v[96:111], v[114:119], v[126:131], v[96:111], v162, v162 op_sel_hi:[0,0,0] cbsz:2 blgp:2
	v_exp_f32_e32 v113, v156
	v_exp_f32_e32 v114, v157
	v_exp_f32_e32 v115, v154
	v_exp_f32_e32 v116, v155
	v_exp_f32_e32 v117, v152
	v_mfma_scale_f32_32x32x64_f8f6f4 v[80:95], v[198:203], v[126:131], v[80:95], v162, v162 op_sel_hi:[0,0,0] cbsz:2 blgp:2
	v_exp_f32_e32 v118, v153
	s_waitcnt lgkmcnt(0)
	v_exp_f32_e32 v119, v150
	v_mfma_scale_f32_32x32x64_f8f6f4 v[96:111], v[66:71], v[132:137], v[96:111], v162, v162 op_sel_hi:[0,0,0] cbsz:2 blgp:2
	v_exp_f32_e32 v156, v151
	v_exp_f32_e32 v157, v148
	v_exp_f32_e32 v215, v149
	v_mfma_scale_f32_32x32x64_f8f6f4 v[80:95], v[72:77], v[132:137], v[80:95], v162, v162 op_sel_hi:[0,0,0] cbsz:2 blgp:2
	s_add_i32 s8, s14, 0xf762bc00
	s_and_b32 s8, s8, 0x6000
	v_add_u32_e32 v64, s8, v173
	ds_read_b128 v[72:75], v64 offset:36864
	ds_read_b128 v[76:79], v64 offset:37376
	ds_read_b128 v[148:151], v64 offset:38912
	ds_read_b128 v[152:155], v64 offset:39424
	ds_read_b128 v[198:201], v64 offset:40960
	ds_read_b128 v[202:205], v64 offset:41472
	ds_read_b128 v[206:209], v64 offset:43008
	ds_read_b128 v[210:213], v64 offset:43520
	v_cvt_pk_fp8_f32 v64, v65, v197
	v_cvt_pk_fp8_f32 v68, v160, v161
	v_cvt_pk_fp8_f32 v65, v195, v196
	v_cvt_pk_fp8_f32 v69, v182, v214
	v_cvt_pk_fp8_f32 v66, v193, v194
	v_cvt_pk_fp8_f32 v70, v115, v116
	v_cvt_pk_fp8_f32 v67, v188, v190
	v_cvt_pk_fp8_f32 v71, v119, v156
	v_cvt_pk_fp8_f32 v64, v187, v189 op_sel:[0,0,1]
	v_cvt_pk_fp8_f32 v68, v158, v159 op_sel:[0,0,1]
	v_cvt_pk_fp8_f32 v65, v191, v192 op_sel:[0,0,1]
	v_cvt_pk_fp8_f32 v69, v113, v114 op_sel:[0,0,1]
	v_cvt_pk_fp8_f32 v66, v183, v184 op_sel:[0,0,1]
	v_cvt_pk_fp8_f32 v70, v117, v118 op_sel:[0,0,1]
	v_cvt_pk_fp8_f32 v67, v185, v186 op_sel:[0,0,1]
	v_cvt_pk_fp8_f32 v71, v157, v215 op_sel:[0,0,1]
	s_waitcnt lgkmcnt(0)
; DEVINL int crow(int r, int hi) { return (r & 3) + 8 * (r >> 2) + 4 * hi; }
; #define SBAR() __builtin_amdgcn_sched_barrier(0)
; #define PVM(db) do { const i32x8 b = {(int)f.v[db][0][0], (int)f.v[db][0][1], (int)f.v[db][0][2], (int)f.v[db][0][3], (int)f.v[db][1][0], (int)f.v[db][1][1], (int)f.v[db][1][2], (int)f.v[db][1][3]}; \
;     o[db] = MFMA8(pa, b, o[db]); } while (0)
; DEVINL void pv_psm(f32x16* o, const VFrag& f, const i32x8& pa, f32x16& lsum, const i32x8& ones8,
;                    f32x16& p0, f32x16& p1, float& m_reg, float& mn, float& alpha, int kvalid, int hi) {
;     ...
;   if (kvalid < 64) {
; #pragma unroll
;     for (int r = 0; r < 16; ++r) { if (crow(r, hi) >= kvalid) p0[r] = -1e30f; if (32 + crow(r, hi) >= kvalid) p1[r] = -1e30f; }
;   }
;   PVM(0);
;   float pmax = p0[0];
; #pragma unroll
;   for (int r = 1; r < 16; ++r) pmax = fmaxf(pmax, p0[r]);
;   SBAR();
;   PVM(1);
; #pragma unroll
;   for (int r = 0; r < 16; ++r) pmax = fmaxf(pmax, p1[r]);
;   { auto rr = __builtin_amdgcn_permlane32_swap(__float_as_uint(pmax), __float_as_uint(pmax), false, false);
;     pmax = fmaxf(__uint_as_float(rr[0]), __uint_as_float(rr[1])); }
;   SBAR();
;   PVM(2);
;   if (__builtin_expect(__all(pmax - m_reg <= THR / MLA_SCALE), 1)) { mn = m_reg; alpha = 1.f; }
;   else { mn = fmaxf(m_reg, pmax); alpha = __builtin_amdgcn_exp2f((m_reg - mn) * C); m_reg = mn; }
; DEVINL void mla_block(const Params& p, const bf16_t* __restrict__ Qn, const bf16_t* __restrict__ Qr, const char* __restrict__ K8, const char* __restrict__ Kp8,
;                       const char* __restrict__ V8, const bf16_t* __restrict__ Gb, bf16_t* __restrict__ Yb, char* lds, int pos0) {
;     ...
;     qkt<true>(pA0, pA1, KS(j + 1), q8, r32, hi, pB1);
	s_nop 0
	v_mfma_scale_f32_32x32x64_f8f6f4 v[0:15], v[64:71], v[72:79], v[0:15], v162, v162 op_sel_hi:[0,0,0]
	v_max_f32_e32 v113, v96, v97
	v_max3_f32 v113, v113, v98, v99
	v_max3_f32 v113, v113, v100, v101
	v_max3_f32 v113, v113, v102, v103
	v_max3_f32 v113, v113, v104, v105
	v_max3_f32 v113, v113, v106, v107
	v_max3_f32 v113, v113, v108, v109
	v_max3_f32 v113, v113, v110, v111
	v_mfma_scale_f32_32x32x64_f8f6f4 v[48:63], v[64:71], v[148:155], v[48:63], v162, v162 op_sel_hi:[0,0,0]
	v_max3_f32 v72, v113, v80, v81
	v_max3_f32 v72, v72, v82, v83
	v_max3_f32 v72, v72, v84, v85
	v_max3_f32 v72, v72, v86, v87
	v_max3_f32 v72, v72, v88, v89
	v_max3_f32 v72, v72, v90, v91
	v_max3_f32 v72, v72, v92, v93
	v_max3_f32 v72, v72, v94, v95
	v_mov_b32_e32 v73, v72
	s_nop 1
	v_permlane32_swap_b32_e32 v72, v73
	v_max_f32_e32 v72, v72, v73
	v_mfma_scale_f32_32x32x64_f8f6f4 v[16:31], v[64:71], v[198:205], v[16:31], v162, v162 op_sel_hi:[0,0,0]
	v_max_f32_e32 v148, v181, v72
	v_sub_f32_e32 v73, v72, v181
	v_sub_f32_e32 v72, v181, v148
	v_mul_f32_e32 v72, 0x3dd53b94, v72
	v_exp_f32_e32 v72, v72
	v_cmp_ge_f32_e32 vcc, s69, v73
	s_cmp_eq_u64 vcc, exec
	s_cselect_b64 s[8:9], -1, 0
	v_cndmask_b32_e64 v182, v72, 1.0, s[8:9]
	v_mfma_scale_f32_32x32x64_f8f6f4 v[32:47], v[64:71], v[206:213], v[32:47], v162, v162 op_sel_hi:[0,0,0]
	v_mfma_scale_f32_32x32x64_f8f6f4 v[240:255], v[232:239], v[64:71], 0, v162, v162 op_sel_hi:[0,0,0]
	s_mulk_i32 s20, 0x2400
	v_add_u32_e32 v174, s20, v173
	v_add_u32_e32 v175, s20, v176
	ds_read_b128 v[200:203], v174
	ds_read_b64 v[204:205], v175
	ds_read_b128 v[206:209], v174 offset:512
	ds_read_b64 v[210:211], v175 offset:256
	v_cmp_gt_f32_e32 vcc, 1.0, v182
	s_cbranch_vccz .LBB0_572
	s_and_saveexec_b64 s[16:17], s[6:7]
	ds_write_b32 v178, v182 offset:128
	s_or_b64 exec, exec, s[16:17]
	s_waitcnt lgkmcnt(0)
	v_add_u32_e32 v113, v171, v177
	ds_read_b128 v[72:75], v113 offset:224
	ds_read_b128 v[76:79], v113 offset:192
	ds_read_b128 v[114:117], v113 offset:160
	ds_read_b128 v[150:153], v113 offset:128
	s_waitcnt lgkmcnt(0)
	v_pk_mul_f32 v[12:13], v[12:13], v[72:73]
	v_pk_mul_f32 v[8:9], v[8:9], v[76:77]
	v_pk_mul_f32 v[4:5], v[4:5], v[114:115]
	v_pk_mul_f32 v[14:15], v[14:15], v[74:75]
	v_pk_mul_f32 v[10:11], v[10:11], v[78:79]
	v_pk_mul_f32 v[6:7], v[6:7], v[116:117]
	v_pk_mul_f32 v[2:3], v[2:3], v[152:153]
	v_pk_mul_f32 v[0:1], v[0:1], v[150:151]
	v_pk_mul_f32 v[60:61], v[60:61], v[72:73]
	v_pk_mul_f32 v[56:57], v[56:57], v[76:77]
	v_pk_mul_f32 v[52:53], v[52:53], v[114:115]
	v_pk_mul_f32 v[62:63], v[62:63], v[74:75]
	v_pk_mul_f32 v[58:59], v[58:59], v[78:79]
	v_pk_mul_f32 v[54:55], v[54:55], v[116:117]
	v_pk_mul_f32 v[50:51], v[50:51], v[152:153]
	v_pk_mul_f32 v[48:49], v[48:49], v[150:151]
	v_pk_mul_f32 v[28:29], v[28:29], v[72:73]
	v_pk_mul_f32 v[24:25], v[24:25], v[76:77]
	v_pk_mul_f32 v[20:21], v[20:21], v[114:115]
	v_pk_mul_f32 v[30:31], v[30:31], v[74:75]
	v_pk_mul_f32 v[26:27], v[26:27], v[78:79]
	v_pk_mul_f32 v[22:23], v[22:23], v[116:117]
	v_pk_mul_f32 v[18:19], v[18:19], v[152:153]
	v_pk_mul_f32 v[16:17], v[16:17], v[150:151]
	v_pk_mul_f32 v[44:45], v[44:45], v[72:73]
	v_pk_mul_f32 v[40:41], v[40:41], v[76:77]
	v_pk_mul_f32 v[36:37], v[36:37], v[114:115]
	v_pk_mul_f32 v[46:47], v[46:47], v[74:75]
	v_pk_mul_f32 v[42:43], v[42:43], v[78:79]
	v_pk_mul_f32 v[38:39], v[38:39], v[116:117]
	v_pk_mul_f32 v[34:35], v[34:35], v[152:153]
	v_pk_mul_f32 v[32:33], v[32:33], v[150:151]
; #define SBAR() __builtin_amdgcn_sched_barrier(0)
; DEVINL i32x8 mk6(int a, int b, int c, int d, int e, int f) { i32x8 r = __builtin_nondeterministic_value(r); r[0] = a; r[1] = b; r[2] = c; r[3] = d; r[4] = e; r[5] = f; return r; }
; #define MFMA6(A, B, C) __builtin_amdgcn_mfma_scale_f32_32x32x64_f8f6f4(A, B, C, 2, 2, 0, 0x7f7f7f7f, 0, 0x7f7f7f7f)
; #define LUPD(al) do { l_reg = l_reg * (al) + lsum[0]; } while (0)
; template <bool FUSE>
; DEVINL void qkt(f32x16& p0, f32x16& p1, const char* Ks, const i32x8* q8, int r32, int hi, f32x16& e1) {
;   p0 = f32x16{}; p1 = f32x16{};
;   const char* ka = Ks + hi * 1024 + r32 * 16; const char* kb = Ks + 4096 + hi * 512 + r32 * 8;
;   const char* ra = Ks + 6144 + hi * 1024 + r32 * 16; const char* rb = Ks + 6144 + 2048 + hi * 512 + r32 * 8;
;   u32x4 fa[3][2]; u32x2 fb[3][2];
;     ...
;   QK_LD(0, 0);
; #pragma unroll
;   for (int t = 0; t < 3; ++t) {
;     if (t + 1 < 3) QK_LD(t + 1, (t + 1) % 3);
;     const i32x8 a0 = mk6((int)fa[t][0][0], (int)fa[t][0][1], (int)fa[t][0][2], (int)fa[t][0][3], (int)fb[t][0][0], (int)fb[t][0][1]);
;     const i32x8 a1 = mk6((int)fa[t][1][0], (int)fa[t][1][1], (int)fa[t][1][2], (int)fa[t][1][3], (int)fb[t][1][0], (int)fb[t][1][1]);
;     p0 = MFMA6(a0, q8[t], p0);
;     if (FUSE) {
; #pragma unroll
;       for (int r = 0; r < 3; ++r) { const int rr = t * 6 + r; if (rr < 16) e1[rr] = __builtin_amdgcn_exp2f(e1[rr]); }
;     }
;     p1 = MFMA6(a1, q8[t], p1);
;     if (FUSE) {
; #pragma unroll
;       for (int r = 3; r < 6; ++r) { const int rr = t * 6 + r; if (rr < 16) e1[rr] = __builtin_amdgcn_exp2f(e1[rr]); }
;     }
;     SBAR();
;   }
;     ...
; }
; DEVINL void mla_block(const Params& p, const bf16_t* __restrict__ Qn, const bf16_t* __restrict__ Qr, const char* __restrict__ K8, const char* __restrict__ Kp8,
;                       const char* __restrict__ V8, const bf16_t* __restrict__ Gb, bf16_t* __restrict__ Yb, char* lds, int pos0) {
;     ...
;     qkt<true>(pA0, pA1, KS(j + 1), q8, r32, hi, pB1);
;     pv_load(vf, VS(j), r32, hi); SBAR();
;     finishSM<true>(pB0, pB1, alB, l_reg, pa); SBAR();
;     { const float alPrev = alB; pv_psm(o, vf, pa, lsum, ones8, pA0, pA1, m_reg, mnA, alA, L - (j + 1) * KVBLK, hi); LUPD(alPrev); }
.LBB0_572:
	v_cndmask_b32_e64 v227, v148, v181, s[8:9]
	v_fmamk_f32 v230, v227, 0xbdd53b94, v164
	v_pk_fma_f32 v[76:77], v[104:105], s[50:51], v[230:231] op_sel_hi:[1,0,0]
	v_pk_fma_f32 v[68:69], v[96:97], s[50:51], v[230:231] op_sel_hi:[1,0,0]
	v_exp_f32_e32 v198, v77
	v_pk_fma_f32 v[70:71], v[98:99], s[50:51], v[230:231] op_sel_hi:[1,0,0]
	v_pk_fma_f32 v[72:73], v[100:101], s[50:51], v[230:231] op_sel_hi:[1,0,0]
	v_pk_fma_f32 v[74:75], v[102:103], s[50:51], v[230:231] op_sel_hi:[1,0,0]
	v_pk_fma_f32 v[78:79], v[106:107], s[50:51], v[230:231] op_sel_hi:[1,0,0]
	v_pk_fma_f32 v[96:97], v[108:109], s[50:51], v[230:231] op_sel_hi:[1,0,0]
	v_pk_fma_f32 v[98:99], v[110:111], s[50:51], v[230:231] op_sel_hi:[1,0,0]
	v_pk_fma_f32 v[102:103], v[80:81], s[50:51], v[230:231] op_sel_hi:[1,0,0]
	v_pk_fma_f32 v[114:115], v[82:83], s[50:51], v[230:231] op_sel_hi:[1,0,0]
	v_pk_fma_f32 v[116:117], v[84:85], s[50:51], v[230:231] op_sel_hi:[1,0,0]
	v_pk_fma_f32 v[228:229], v[86:87], s[50:51], v[230:231] op_sel_hi:[1,0,0]
	v_pk_fma_f32 v[156:157], v[88:89], s[50:51], v[230:231] op_sel_hi:[1,0,0]
	v_exp_f32_e32 v113, v68
	v_exp_f32_e32 v181, v69
	v_exp_f32_e32 v183, v70
	v_exp_f32_e32 v192, v71
	v_exp_f32_e32 v193, v72
	v_exp_f32_e32 v194, v73
	v_exp_f32_e32 v195, v74
	v_exp_f32_e32 v196, v75
	v_exp_f32_e32 v197, v76
	v_exp_f32_e32 v199, v78
	v_exp_f32_e32 v216, v79
	v_exp_f32_e32 v217, v96
	v_exp_f32_e32 v218, v97
	v_exp_f32_e32 v219, v98
	v_exp_f32_e32 v220, v99
	v_pk_fma_f32 v[158:159], v[90:91], s[50:51], v[230:231] op_sel_hi:[1,0,0]
	v_pk_fma_f32 v[160:161], v[92:93], s[50:51], v[230:231] op_sel_hi:[1,0,0]
	v_pk_fma_f32 v[184:185], v[94:95], s[50:51], v[230:231] op_sel_hi:[1,0,0]
	ds_read_b128 v[98:101], v174 offset:2048
	ds_read_b128 v[104:107], v174 offset:2560
	v_exp_f32_e32 v221, v102
	v_exp_f32_e32 v222, v103
	ds_read_b64 v[102:103], v175 offset:1024
	ds_read_b64 v[108:109], v175 offset:1280
	s_waitcnt lgkmcnt(4)
	v_mfma_scale_f32_32x32x64_f8f6f4 v[66:81], v[200:205], v[120:125], 0, v162, v162 op_sel_hi:[0,0,0] cbsz:2 blgp:2
	v_exp_f32_e32 v223, v114
	v_exp_f32_e32 v224, v115
	v_exp_f32_e32 v225, v116
	v_exp_f32_e32 v226, v117
	v_mfma_scale_f32_32x32x64_f8f6f4 v[82:97], v[206:211], v[120:125], 0, v162, v162 op_sel_hi:[0,0,0] cbsz:2 blgp:2
	ds_read_b128 v[114:117], v174 offset:6144
	ds_read_b128 v[148:151], v174 offset:6656
	ds_read_b64 v[118:119], v175 offset:4096
	ds_read_b64 v[152:153], v175 offset:4352
	s_waitcnt lgkmcnt(4)
	v_mfma_scale_f32_32x32x64_f8f6f4 v[66:81], v[98:103], v[126:131], v[66:81], v162, v162 op_sel_hi:[0,0,0] cbsz:2 blgp:2
	v_exp_f32_e32 v100, v228
	v_exp_f32_e32 v101, v229
	v_exp_f32_e32 v110, v156
	v_exp_f32_e32 v111, v157
	v_exp_f32_e32 v156, v158
	v_exp_f32_e32 v157, v159
	v_mfma_scale_f32_32x32x64_f8f6f4 v[82:97], v[104:109], v[126:131], v[82:97], v162, v162 op_sel_hi:[0,0,0] cbsz:2 blgp:2
	s_waitcnt lgkmcnt(0)
	v_exp_f32_e32 v106, v160
	v_mfma_scale_f32_32x32x64_f8f6f4 v[66:81], v[114:119], v[132:137], v[66:81], v162, v162 op_sel_hi:[0,0,0] cbsz:2 blgp:2
	v_exp_f32_e32 v107, v161
	v_exp_f32_e32 v108, v184
	v_exp_f32_e32 v109, v185
	v_mfma_scale_f32_32x32x64_f8f6f4 v[82:97], v[148:153], v[132:137], v[82:97], v162, v162 op_sel_hi:[0,0,0] cbsz:2 blgp:2
	v_lshl_add_u32 v98, s12, 13, v173
	ds_read_b128 v[148:151], v98 offset:36864
	ds_read_b128 v[152:155], v98 offset:37376
	ds_read_b128 v[184:187], v98 offset:38912
	ds_read_b128 v[188:191], v98 offset:39424
	ds_read_b128 v[200:203], v98 offset:40960
	ds_read_b128 v[204:207], v98 offset:41472
	ds_read_b128 v[208:211], v98 offset:43008
	ds_read_b128 v[212:215], v98 offset:43520
	v_cvt_pk_fp8_f32 v103, v225, v226
	v_cvt_pk_fp8_f32 v98, v113, v181
	v_cvt_pk_fp8_f32 v102, v221, v222
	v_cvt_pk_fp8_f32 v99, v193, v194
	v_cvt_pk_fp8_f32 v103, v100, v101 op_sel:[0,0,1]
	v_cvt_pk_fp8_f32 v100, v197, v198
	v_cvt_pk_fp8_f32 v104, v110, v111
	v_cvt_pk_fp8_f32 v101, v217, v218
	v_cvt_pk_fp8_f32 v105, v106, v107
	v_cvt_pk_fp8_f32 v98, v183, v192 op_sel:[0,0,1]
	v_cvt_pk_fp8_f32 v102, v223, v224 op_sel:[0,0,1]
	v_cvt_pk_fp8_f32 v99, v195, v196 op_sel:[0,0,1]
	v_cvt_pk_fp8_f32 v100, v199, v216 op_sel:[0,0,1]
	v_cvt_pk_fp8_f32 v104, v156, v157 op_sel:[0,0,1]
	v_cvt_pk_fp8_f32 v101, v219, v220 op_sel:[0,0,1]
	v_cvt_pk_fp8_f32 v105, v108, v109 op_sel:[0,0,1]
	s_waitcnt lgkmcnt(0)
	s_nop 0
	v_mfma_scale_f32_32x32x64_f8f6f4 v[0:15], v[98:105], v[148:155], v[0:15], v162, v162 op_sel_hi:[0,0,0]
	s_cmpk_gt_u32 s19, 0xff
	s_cbranch_scc1 .Lmask_last

; #define TILE_SYNC() do { asm volatile("s_waitcnt vmcnt(0)" ::: "memory"); __syncthreads(); } while (0)
; #define RESC(a) do { if (__any((a) < 1.f)) { if (hi == 0) al_l[r32] = (a); asm volatile("s_waitcnt lgkmcnt(0)" ::: "memory"); \
;     for (int d = 0; d < 4; ++d) for (int r = 0; r < 16; ++r) o[d][r] *= al_l[crow(r, hi)]; } } while (0)
; #define LUPD(al) do { l_reg = l_reg * (al) + lsum[0]; } while (0)
; template <bool FUSE>
; DEVINL void qkt(f32x16& p0, f32x16& p1, const char* Ks, const i32x8* q8, int r32, int hi, f32x16& e1) {
;   p0 = f32x16{}; p1 = f32x16{};
;   const char* ka = Ks + hi * 1024 + r32 * 16; const char* kb = Ks + 4096 + hi * 512 + r32 * 8;
;   const char* ra = Ks + 6144 + hi * 1024 + r32 * 16; const char* rb = Ks + 6144 + 2048 + hi * 512 + r32 * 8;
;   u32x4 fa[3][2]; u32x2 fb[3][2];
; DEVINL void mla_block(const Params& p, const bf16_t* __restrict__ Qn, const bf16_t* __restrict__ Qr, const char* __restrict__ K8, const char* __restrict__ Kp8,
;                       const char* __restrict__ V8, const bf16_t* __restrict__ Gb, bf16_t* __restrict__ Yb, char* lds, int pos0) {
;     ...
;     { const float alPrev = alB; pv_psm(o, vf, pa, lsum, ones8, pA0, pA1, m_reg, mnA, alA, L - (j + 1) * KVBLK, hi); LUPD(alPrev); }
;     TILE_SYNC(); RESC(alA);
;   }
.LBB0_576:
	s_add_i32 s16, s53, -1
	s_and_b32 s16, s16, 3
	s_mul_i32 s16, s16, 0x2400
	v_add_u32_e32 v174, s16, v173
	v_add_u32_e32 v175, s16, v176
	ds_read_b128 v[204:207], v174
	ds_read_b64 v[208:209], v175
	ds_read_b128 v[216:219], v174 offset:512
	ds_read_b64 v[220:221], v175 offset:256
	v_cndmask_b32_e64 v181, v241, v227, s[8:9]
	v_fmamk_f32 v230, v181, 0xbdd53b94, v164
	v_pk_fma_f32 v[228:229], v[74:75], s[50:51], v[230:231] op_sel_hi:[1,0,0]
	v_pk_fma_f32 v[66:67], v[66:67], s[50:51], v[230:231] op_sel_hi:[1,0,0]
	v_pk_fma_f32 v[68:69], v[68:69], s[50:51], v[230:231] op_sel_hi:[1,0,0]
	v_pk_fma_f32 v[70:71], v[70:71], s[50:51], v[230:231] op_sel_hi:[1,0,0]
	v_pk_fma_f32 v[72:73], v[72:73], s[50:51], v[230:231] op_sel_hi:[1,0,0]
	v_pk_fma_f32 v[154:155], v[90:91], s[50:51], v[230:231] op_sel_hi:[1,0,0]
	v_pk_fma_f32 v[152:153], v[92:93], s[50:51], v[230:231] op_sel_hi:[1,0,0]
	v_pk_fma_f32 v[150:151], v[94:95], s[50:51], v[230:231] op_sel_hi:[1,0,0]
	v_pk_fma_f32 v[148:149], v[96:97], s[50:51], v[230:231] op_sel_hi:[1,0,0]
	v_exp_f32_e32 v65, v66
	v_exp_f32_e32 v197, v67
	v_exp_f32_e32 v187, v68
	v_exp_f32_e32 v189, v69
	v_exp_f32_e32 v195, v70
	v_exp_f32_e32 v196, v71
	v_exp_f32_e32 v191, v72
	v_exp_f32_e32 v192, v73
	v_fma_f32 v180, v179, v180, v240
	v_mfma_scale_f32_32x32x64_f8f6f4 v[240:255], v[232:239], v[98:105], 0, v162, v162 op_sel_hi:[0,0,0]
	v_fma_f32 v94, v76, s50, v230
	v_fma_f32 v95, v77, s50, v230
	v_fma_f32 v96, v78, s50, v230
	v_fma_f32 v97, v79, s50, v230
	v_fma_f32 v106, v80, s50, v230
	v_fma_f32 v107, v81, s50, v230
	v_exp_f32_e32 v193, v228
	v_exp_f32_e32 v194, v229
	v_exp_f32_e32 v183, v94
	v_exp_f32_e32 v184, v95
	v_exp_f32_e32 v188, v96
	v_exp_f32_e32 v190, v97
	v_exp_f32_e32 v185, v106
	v_exp_f32_e32 v186, v107
	s_add_i32 s53, s53, 2
	s_add_u32 s14, s14, 0x4000
	s_addc_u32 s15, s15, 0
	v_pk_fma_f32 v[160:161], v[82:83], s[50:51], v[230:231] op_sel_hi:[1,0,0]
	v_pk_fma_f32 v[158:159], v[84:85], s[50:51], v[230:231] op_sel_hi:[1,0,0]
	v_pk_fma_f32 v[82:83], v[86:87], s[50:51], v[230:231] op_sel_hi:[1,0,0]
	v_pk_fma_f32 v[156:157], v[88:89], s[50:51], v[230:231] op_sel_hi:[1,0,0]
	s_cmpk_gt_u32 s18, 0xfd
	v_fma_f32 v180, v182, v180, v240
	s_cbranch_scc1 .LBB0_578
	v_mov_b32_e32 v179, v198
	s_branch .LBB0_560

; #define SBAR() __builtin_amdgcn_sched_barrier(0)
; #define LSUM() do { lsum = MFMA8(ones8, pa, (f32x16{})); } while (0)
; #define LUPD(al) do { l_reg = l_reg * (al) + lsum[0]; } while (0)
; DEVINL void mla_block(const Params& p, const bf16_t* __restrict__ Qn, const bf16_t* __restrict__ Qr, const char* __restrict__ K8, const char* __restrict__ Kp8,
;                       const char* __restrict__ V8, const bf16_t* __restrict__ Gb, bf16_t* __restrict__ Yb, char* lds, int pos0) {
;     ...
;   pv_load(vf, VS(NT - 1), r32, hi); SBAR();
;   finishSM<false>(pA0, pA1, alA, l_reg, pa); SBAR();
;   pv_mma(o, vf, pa); LSUM(); LUPD(alA);
;   if (hi == 0) li_l[r32] = l_reg; asm volatile("s_waitcnt lgkmcnt(0)" ::: "memory");
.LBB0_578:
	s_setprio 0
	ds_read_b128 v[128:131], v173 offset:36864
	ds_read_b128 v[132:135], v173 offset:37376
	ds_read_b128 v[120:123], v173 offset:38912
	ds_read_b128 v[124:127], v173 offset:39424
	ds_read_b128 v[92:95], v173 offset:40960
	ds_read_b128 v[96:99], v173 offset:41472
	ds_read_b128 v[84:87], v173 offset:43008
	ds_read_b128 v[88:91], v173 offset:43520
	v_exp_f32_e32 v64, v160
	v_exp_f32_e32 v67, v161
	v_exp_f32_e32 v70, v82
	v_exp_f32_e32 v71, v83
	v_exp_f32_e32 v74, v154
	v_exp_f32_e32 v75, v155
	v_exp_f32_e32 v78, v150
	v_exp_f32_e32 v79, v151
	v_mov_b32_e32 v100, v139
	v_mov_b32_e32 v104, v139
	v_mov_b32_e32 v101, v139
	v_mov_b32_e32 v105, v139
	v_mov_b32_e32 v102, v139
	v_mov_b32_e32 v106, v139
	v_mov_b32_e32 v103, v139
	v_mov_b32_e32 v107, v139
	v_exp_f32_e32 v68, v158
	v_exp_f32_e32 v69, v159
	v_exp_f32_e32 v72, v156
	v_exp_f32_e32 v73, v157
	v_exp_f32_e32 v76, v152
	v_exp_f32_e32 v77, v153
	v_exp_f32_e32 v80, v148
	v_exp_f32_e32 v81, v149
	v_cvt_pk_fp8_f32 v100, v65, v197
	v_cvt_pk_fp8_f32 v104, v64, v67
	v_cvt_pk_fp8_f32 v101, v195, v196
	v_cvt_pk_fp8_f32 v105, v70, v71
	v_cvt_pk_fp8_f32 v102, v193, v194
	v_cvt_pk_fp8_f32 v106, v74, v75
	v_cvt_pk_fp8_f32 v103, v188, v190
	v_cvt_pk_fp8_f32 v107, v78, v79
	v_cvt_pk_fp8_f32 v100, v187, v189 op_sel:[0,0,1]
	v_cvt_pk_fp8_f32 v104, v68, v69 op_sel:[0,0,1]
	v_cvt_pk_fp8_f32 v101, v191, v192 op_sel:[0,0,1]
	v_cvt_pk_fp8_f32 v105, v72, v73 op_sel:[0,0,1]
	v_cvt_pk_fp8_f32 v102, v183, v184 op_sel:[0,0,1]
	v_cvt_pk_fp8_f32 v106, v76, v77 op_sel:[0,0,1]
	v_cvt_pk_fp8_f32 v103, v185, v186 op_sel:[0,0,1]
	v_cvt_pk_fp8_f32 v107, v80, v81 op_sel:[0,0,1]
	s_and_saveexec_b64 s[4:5], s[6:7]
	s_cbranch_execz .LBB0_549
	v_mov_b32_e32 v113, v112
	v_mov_b32_e32 v114, v112
	v_mov_b32_e32 v115, v112
	v_mov_b32_e32 v116, v112
	v_mov_b32_e32 v117, v112
	v_mov_b32_e32 v118, v112
	v_mov_b32_e32 v119, v112
	s_nop 1
	v_mfma_scale_f32_32x32x64_f8f6f4 v[68:83], v[232:239], v[100:107], 0, v162, v162 op_sel_hi:[0,0,0]
	s_nop 15
	s_nop 3
	v_fmac_f32_e32 v68, v198, v180
	ds_write_b32 v178, v68
	s_branch .LBB0_549
